# v12 with the scan-phase conversion rewritten without the LDS transpose (per-lane 16 row loads of one column, pipelined across loader iterations)
# baseline (speedup 1.0000x reference)
.LBB0_190:
	v_readfirstlane_b32 s13, v160
	s_ashr_i32 s13, s13, 6
	s_cmp_gt_i32 s13, 3
	s_mov_b64 s[14:15], -1
	s_cbranch_scc0 .LBB0_219
	s_load_dwordx2 s[50:51], s[28:29], 0xa8
	s_load_dwordx2 s[52:53], s[28:29], 0xd0
	s_load_dwordx2 s[58:59], s[28:29], 0xc0
	s_load_dwordx2 s[60:61], s[28:29], 0xb8
	s_load_dwordx2 s[62:63], s[28:29], 0xc8
	s_load_dwordx2 s[64:65], s[28:29], 0xb0
	s_load_dwordx2 s[66:67], s[28:29], 0xf0
	v_readlane_b32 s56, v254, 22
	v_lshrrev_b32_e32 v222, 3, v197
	v_and_b32_e32 v223, 7, v197
	v_lshlrev_b32_e32 v217, 2, v222
	v_mul_u32_u24_e32 v218, 33, v222
	v_lshl_add_u32 v218, v223, 2, v218
	v_lshlrev_b32_e32 v218, 2, v218
	v_and_b32_e32 v223, 3, v197
	v_lshrrev_b32_e32 v222, 2, v197
	v_mul_u32_u24_e32 v219, 0x108, v223
	v_add_lshl_u32 v219, v219, v222, 2
	s_sub_u32 s57, s13, 4
	s_mul_i32 s55, s57, 0x1080
	s_add_u32 s55, s55, 0x16000
	v_add_u32_e32 v218, s55, v218
	v_add_u32_e32 v219, s55, v219
	v_readlane_b32 s55, v253, 0
	s_lshl_b32 s55, s55, 2
	s_add_u32 s55, s55, s57
	s_waitcnt lgkmcnt(0)
	s_lshl_b32 s57, s56, 24
	s_add_u32 s50, s50, s57
	s_addc_u32 s51, s51, 0
	v_writelane_b32 v224, s50, 0
	v_writelane_b32 v224, s51, 1
	s_lshl_b32 s57, s56, 24
	s_add_u32 s52, s52, s57
	s_addc_u32 s53, s53, 0
	v_writelane_b32 v224, s52, 2
	v_writelane_b32 v224, s53, 3
	s_lshl_b32 s57, s56, 26
	s_add_u32 s58, s58, s57
	s_addc_u32 s59, s59, 0
	v_writelane_b32 v224, s58, 4
	v_writelane_b32 v224, s59, 5
	s_lshl_b32 s57, s56, 26
	s_add_u32 s60, s60, s57
	s_addc_u32 s61, s61, 0
	v_writelane_b32 v224, s60, 6
	v_writelane_b32 v224, s61, 7
	s_lshl_b32 s57, s56, 13
	s_add_u32 s62, s62, s57
	s_addc_u32 s63, s63, 0
	v_writelane_b32 v224, s62, 8
	v_writelane_b32 v224, s63, 9
	s_lshl_b32 s57, s56, 13
	s_add_u32 s64, s64, s57
	s_addc_u32 s65, s65, 0
	v_writelane_b32 v224, s64, 10
	v_writelane_b32 v224, s65, 11
	s_lshl_b32 s57, s56, 23
	s_add_u32 s50, s66, s57
	s_addc_u32 s51, s67, 0
	s_add_u32 s50, s50, 0x4900000
	s_addc_u32 s51, s51, 0
	v_writelane_b32 v224, s50, 12
	v_writelane_b32 v224, s51, 13
	s_lshl_b32 s57, s56, 23
	s_add_u32 s50, s66, s57
	s_addc_u32 s51, s67, 0
	s_add_u32 s50, s50, 0x16900000
	s_addc_u32 s51, s51, 0
	v_writelane_b32 v224, s50, 14
	v_writelane_b32 v224, s51, 15
	s_lshl_b32 s57, s56, 25
	s_add_u32 s50, s66, s57
	s_addc_u32 s51, s67, 0
	s_add_u32 s50, s50, 0xe900000
	s_addc_u32 s51, s51, 0
	v_writelane_b32 v224, s50, 16
	v_writelane_b32 v224, s51, 17
	s_lshl_b32 s57, s56, 25
	s_add_u32 s50, s66, s57
	s_addc_u32 s51, s67, 0
	s_add_u32 s50, s50, 0x6900000
	s_addc_u32 s51, s51, 0
	v_writelane_b32 v224, s50, 18
	v_writelane_b32 v224, s51, 19
	s_load_dwordx2 s[50:51], s[28:29], 0x8
	s_load_dwordx2 s[52:53], s[28:29], 0x18
	s_load_dwordx2 s[58:59], s[28:29], 0x10
	s_waitcnt lgkmcnt(0)
	s_lshl_b32 s57, s56, 24
	s_add_u32 s50, s50, s57
	s_addc_u32 s51, s51, 0
	v_writelane_b32 v224, s50, 20
	v_writelane_b32 v224, s51, 21
	s_lshl_b32 s57, s56, 23
	s_add_u32 s60, s66, s57
	s_addc_u32 s61, s67, 0
	s_add_u32 s60, s60, 0x19b00000
	s_addc_u32 s61, s61, 0
	v_writelane_b32 v224, s60, 22
	v_writelane_b32 v224, s61, 23
	s_add_u32 s57, s56, 1
	s_mul_i32 s60, s57, 0x2240000
	s_mul_hi_u32 s61, s57, 0x2240000
	s_add_u32 s52, s52, s60
	s_addc_u32 s53, s53, s61
	v_writelane_b32 v224, s52, 24
	v_writelane_b32 v224, s53, 25
	s_lshl_b32 s60, s57, 13
	s_add_u32 s58, s58, s60
	s_addc_u32 s59, s59, 0
	v_writelane_b32 v224, s58, 26
	v_writelane_b32 v224, s59, 27
	s_mul_i32 s60, s57, 0x1200000
	s_mul_hi_u32 s61, s57, 0x1200000
	s_add_u32 s60, s60, s66
	s_addc_u32 s61, s61, s67
	s_add_u32 s60, s60, 0x100000
	s_addc_u32 s61, s61, 0
	v_writelane_b32 v224, s60, 28
	v_writelane_b32 v224, s61, 29
	s_mov_b32 s60, 0xb000
	s_cmp_lt_u32 s56, 3
	s_cselect_b32 s60, 0xd240, s60
	v_writelane_b32 v224, s60, 30
	v_lshrrev_b32_e32 v250, 5, v197
	v_lshlrev_b32_e32 v250, 6, v250
	s_mov_b32 s62, 0x7fffffff
	s_mov_b32 s63, 0x20000
	s_mov_b32 s53, 0
	s_load_dwordx2 s[14:15], s[28:29], 0xf0
	s_ashr_i32 s20, s0, 6
	s_ashr_i32 s21, s20, 31
	s_lshl_b32 s16, s0, 4
	s_lshl_b64 s[22:23], s[20:21], 12
	s_and_b32 s16, s16, 0x3c0
	s_waitcnt lgkmcnt(0)
	s_add_u32 s30, s14, 0x28700000
	s_addc_u32 s31, s15, 0
	s_load_dwordx2 s[18:19], s[28:29], 0x20
	s_load_dwordx4 s[44:47], s[28:29], 0x80
	s_add_u32 s34, s14, 0x31700000
	s_addc_u32 s35, s15, 0
	s_add_u32 s24, s14, 0x26700000
	v_readlane_b32 s26, v254, 22
	s_addc_u32 s25, s15, 0
	s_mov_b32 s48, s26
	s_mulk_i32 s26, 0x3480
	v_or_b32_e32 v46, s16, v161
	s_waitcnt lgkmcnt(0)
	s_add_u32 s18, s18, s26
	s_mul_hi_u32 s26, s48, 0x3480
	s_addc_u32 s19, s19, s26
	v_lshlrev_b32_e32 v156, 2, v46
	v_lshl_add_u64 v[0:1], s[18:19], 0, v[156:157]
	global_load_dwordx4 v[28:31], v156, s[18:19] offset:16
	global_load_dwordx4 v[8:11], v156, s[18:19]
	s_mov_b64 s[18:19], 0x1000
	v_lshl_add_u64 v[2:3], v[0:1], 0, s[18:19]
	v_add_co_u32_e32 v4, vcc, s69, v0
	s_mov_b64 s[18:19], 0x2000
	s_nop 0
	v_addc_co_u32_e32 v5, vcc, 0, v1, vcc
	v_lshl_add_u64 v[0:1], v[0:1], 0, s[18:19]
	s_add_u32 s18, s44, s6
	s_addc_u32 s19, s45, s7
	global_load_dwordx4 v[24:27], v[4:5], off offset:-4096
	global_load_dwordx4 v[32:35], v[4:5], off
	global_load_dwordx4 v[20:23], v[2:3], off offset:16
	global_load_dwordx4 v[36:39], v[0:1], off offset:16
	global_load_dwordx4 v[16:19], v156, s[18:19] offset:16
	global_load_dwordx4 v[12:15], v156, s[18:19]
	s_add_u32 s18, s46, s6
	s_addc_u32 s19, s47, s7
	v_lshl_add_u64 v[48:49], s[22:23], 0, v[120:121]
	v_mov_b64_e32 v[42:43], s[30:31]
	global_load_dwordx4 v[0:3], v156, s[18:19] offset:16
	global_load_dwordx4 v[4:7], v156, s[18:19]
	v_mad_u64_u32 v[44:45], s[18:19], v48, s75, v[42:43]
	v_lshl_add_u64 v[40:41], v[48:49], 0, v[122:123]
	v_mad_i32_i24 v45, v49, s75, v45
	v_lshlrev_b32_e32 v156, 1, v46
	v_lshl_add_u64 v[44:45], v[44:45], 0, v[156:157]
	v_mad_u64_u32 v[42:43], s[18:19], v40, s75, v[42:43]
	v_mad_i32_i24 v43, v41, s75, v43
	v_add_co_u32_e32 v40, vcc, s74, v44
	v_lshl_add_u64 v[46:47], v[42:43], 0, v[156:157]
	s_nop 0
	v_addc_co_u32_e32 v41, vcc, 0, v45, vcc
	global_load_dwordx4 v[88:91], v[40:41], off
	s_nop 0
	global_load_dwordx4 v[40:43], v[40:41], off offset:2048
	s_nop 0
	global_load_dwordx4 v[92:95], v[44:45], off offset:2048
	global_load_dwordx4 v[68:71], v[46:47], off offset:2048
	v_add_co_u32_e32 v44, vcc, s74, v46
	v_lshlrev_b64 v[144:145], 11, v[48:49]
	s_nop 0
	v_addc_co_u32_e32 v45, vcc, 0, v47, vcc
	global_load_dwordx4 v[64:67], v[44:45], off
	global_load_dwordx4 v[56:59], v[44:45], off offset:2048
	v_lshl_add_u64 v[44:45], s[34:35], 0, v[144:145]
	s_add_u32 s46, s14, 0x33700000
	v_lshl_add_u64 v[44:45], v[44:45], 0, v[156:157]
	s_addc_u32 s47, s15, 0
	global_load_dwordx4 v[60:63], v[44:45], off
	v_lshl_add_u64 v[44:45], s[46:47], 0, v[144:145]
	v_lshl_add_u64 v[44:45], v[44:45], 0, v[156:157]
	global_load_dwordx4 v[44:47], v[44:45], off
	v_cndmask_b32_e64 v50, 0, 1, s[2:3]
	v_cmp_ne_u32_e64 s[44:45], 1, v50
	s_andn2_b64 vcc, exec, s[2:3]
	v_readlane_b32 s27, v254, 23
	s_waitcnt vmcnt(1)
	v_mov_b64_e32 v[102:103], v[62:63]
	v_mov_b64_e32 v[106:107], v[62:63]
	v_mov_b64_e32 v[100:101], v[60:61]
	v_mov_b64_e32 v[104:105], v[60:61]
	s_cbranch_vccnz .LBB0_193
	v_lshlrev_b64 v[48:49], 10, v[48:49]
	v_lshlrev_b64 v[48:49], 1, v[48:49]
	v_lshl_add_u64 v[50:51], s[14:15], 0, v[48:49]
	v_lshl_add_u64 v[50:51], v[50:51], 0, v[156:157]
	v_add_co_u32_e32 v50, vcc, 0x37700000, v50
	v_lshl_add_u64 v[48:49], s[24:25], 0, v[48:49]
	s_nop 0
	v_addc_co_u32_e32 v51, vcc, 0, v51, vcc
	v_lshl_add_u64 v[48:49], v[48:49], 0, v[156:157]
	global_load_dwordx4 v[100:103], v[50:51], off
	global_load_dwordx4 v[104:107], v[48:49], off

.LBB0_208:
	s_cmp_eq_u32 s53, 1
	s_cbranch_scc0 .Lcis_b_done
	s_waitcnt vmcnt(4)
	s_cmp_eq_u32 s56, 1
	s_cbranch_scc0 .Lcis_b_nogs
	v_pk_mul_f32 v[232:233], v[232:233], v[208:209]
	v_pk_mul_f32 v[234:235], v[234:235], v[210:211]
	v_pk_mul_f32 v[236:237], v[236:237], v[212:213]
	v_pk_mul_f32 v[238:239], v[238:239], v[214:215]
	v_pk_mul_f32 v[240:241], v[240:241], v[216:217]
	v_pk_mul_f32 v[242:243], v[242:243], v[218:219]
	v_pk_mul_f32 v[244:245], v[244:245], v[220:221]
	v_pk_mul_f32 v[246:247], v[246:247], v[222:223]
.Lcis_b_nogs:
	v_cvt_pk_bf16_f32 v232, v232, v233
	v_cvt_pk_bf16_f32 v233, v234, v235
	v_cvt_pk_bf16_f32 v234, v236, v237
	v_cvt_pk_bf16_f32 v235, v238, v239
	v_cvt_pk_bf16_f32 v236, v240, v241
	v_cvt_pk_bf16_f32 v237, v242, v243
	v_cvt_pk_bf16_f32 v238, v244, v245
	v_cvt_pk_bf16_f32 v239, v246, v247
	global_store_dwordx4 v249, v[232:235], s[64:65]
	s_cmp_eq_u32 s56, 2
	s_cbranch_scc1 .Lcis_b_flat
	global_store_dwordx4 v249, v[236:239], s[64:65] offset:16
	s_branch .Lcis_b_done
.Lcis_b_flat:
	global_store_dwordx4 v249, v[236:239], s[64:65] offset:1024

.Lcis_j_win:
	s_sub_u32 s51, s55, 0xb000
	s_mul_hi_u32 s50, s51, 0x1de5d6f
	s_mul_i32 s52, s50, 137
	s_sub_u32 s51, s51, s52
	s_mov_b32 s57, 0x4480
	s_movk_i32 s56, 1
	s_movk_i32 s66, 12
	v_readlane_b32 s60, v224, 24
	v_readlane_b32 s61, v224, 25
	v_readlane_b32 s64, v224, 28
	v_readlane_b32 s65, v224, 29
	v_readlane_b32 s58, v224, 26
	v_readlane_b32 s59, v224, 27
	s_branch .Lcis_j_common
.Lcis_j_up:
	s_sub_u32 s51, s55, 0x6000
	s_lshr_b32 s50, s51, 8
	s_and_b32 s51, s51, 0xff
	s_mov_b32 s57, 0x8000
	s_movk_i32 s56, 1
	s_movk_i32 s66, 12
	v_readlane_b32 s60, v224, 6
	v_readlane_b32 s61, v224, 7
	v_readlane_b32 s64, v224, 18
	v_readlane_b32 s65, v224, 19
	v_readlane_b32 s58, v224, 10
	v_readlane_b32 s59, v224, 11
	s_branch .Lcis_j_common
.Lcis_j_down:
	s_sub_u32 s51, s55, 0x2000
	s_lshr_b32 s50, s51, 6
	s_and_b32 s51, s51, 0x3f
	s_mov_b32 s57, 0x2000
	s_movk_i32 s56, 0
	s_movk_i32 s66, 14
	v_readlane_b32 s60, v224, 4
	v_readlane_b32 s61, v224, 5
	v_readlane_b32 s64, v224, 16
	v_readlane_b32 s65, v224, 17
	s_branch .Lcis_j_common
.Lcis_j_gate:
	s_sub_u32 s51, s55, 0x1000
	s_lshr_b32 s50, s51, 6
	s_and_b32 s51, s51, 0x3f
	s_mov_b32 s57, 0x2000
	s_movk_i32 s56, 1
	s_movk_i32 s66, 12
	v_readlane_b32 s60, v224, 2
	v_readlane_b32 s61, v224, 3
	v_readlane_b32 s64, v224, 14
	v_readlane_b32 s65, v224, 15
	v_readlane_b32 s58, v224, 8
	v_readlane_b32 s59, v224, 9
	s_branch .Lcis_j_common
.Lcis_j_wout:
	s_sub_u32 s51, s55, 0x0
	s_lshr_b32 s50, s51, 6
	s_and_b32 s51, s51, 0x3f
	s_mov_b32 s57, 0x2000
	s_movk_i32 s56, 0
	s_movk_i32 s66, 12
	v_readlane_b32 s60, v224, 0
	v_readlane_b32 s61, v224, 1
	v_readlane_b32 s64, v224, 12
	v_readlane_b32 s65, v224, 13
.Lcis_j_common:
	s_lshl_b32 s52, s57, 5
	s_mul_i32 s52, s52, s50
	s_add_u32 s60, s60, s52
	s_addc_u32 s61, s61, 0
	s_lshl_b32 s52, s51, 7
	s_add_u32 s60, s60, s52
	s_addc_u32 s61, s61, 0
	s_and_b32 s61, s61, 0xffff
	s_add_u32 s52, s66, 5
	s_lshl_b32 s52, s51, s52
	s_add_u32 s64, s64, s52
	s_addc_u32 s65, s65, 0
	s_lshl_b32 s52, s50, 6
	s_add_u32 s64, s64, s52
	s_addc_u32 s65, s65, 0
	v_lshrrev_b32_e32 v251, 5, v197
	s_lshl_b32 s52, s57, 4
	v_mul_u32_u24_e32 v248, s52, v251
	v_lshlrev_b32_e32 v249, 5, v251
	v_and_b32_e32 v251, 31, v197
	v_lshl_add_u32 v248, v251, 2, v248
	v_lshlrev_b32_e32 v251, s66, v251
	v_add_u32_e32 v249, v251, v249
	s_mov_b32 s52, 0
	buffer_load_dword v232, v248, s[60:63], s52 offen
	s_add_u32 s52, s52, s57
	buffer_load_dword v233, v248, s[60:63], s52 offen
	s_add_u32 s52, s52, s57
	buffer_load_dword v234, v248, s[60:63], s52 offen
	s_add_u32 s52, s52, s57
	buffer_load_dword v235, v248, s[60:63], s52 offen
	s_add_u32 s52, s52, s57
	buffer_load_dword v236, v248, s[60:63], s52 offen
	s_add_u32 s52, s52, s57
	buffer_load_dword v237, v248, s[60:63], s52 offen
	s_add_u32 s52, s52, s57
	buffer_load_dword v238, v248, s[60:63], s52 offen
	s_add_u32 s52, s52, s57
	buffer_load_dword v239, v248, s[60:63], s52 offen
	s_add_u32 s52, s52, s57
	buffer_load_dword v240, v248, s[60:63], s52 offen
	s_add_u32 s52, s52, s57
	buffer_load_dword v241, v248, s[60:63], s52 offen
	s_add_u32 s52, s52, s57
	buffer_load_dword v242, v248, s[60:63], s52 offen
	s_add_u32 s52, s52, s57
	buffer_load_dword v243, v248, s[60:63], s52 offen
	s_add_u32 s52, s52, s57
	buffer_load_dword v244, v248, s[60:63], s52 offen
	s_add_u32 s52, s52, s57
	buffer_load_dword v245, v248, s[60:63], s52 offen
	s_add_u32 s52, s52, s57
	buffer_load_dword v246, v248, s[60:63], s52 offen
	s_add_u32 s52, s52, s57
	buffer_load_dword v247, v248, s[60:63], s52 offen
	s_cmp_eq_u32 s56, 0
	s_cbranch_scc1 .Lcis_a_inc
	s_lshl_b32 s52, s50, 7
	s_add_u32 s58, s58, s52
	s_addc_u32 s59, s59, 0
	global_load_dwordx4 v[208:211], v250, s[58:59]
	global_load_dwordx4 v[212:215], v250, s[58:59] offset:16
	global_load_dwordx4 v[216:219], v250, s[58:59] offset:32
	global_load_dwordx4 v[220:223], v250, s[58:59] offset:48
	s_branch .Lcis_a_inc
.Lcis_j_p:
	s_sub_u32 s51, s55, 0xa000
	s_movk_i32 s56, 2
	v_readlane_b32 s58, v224, 20
	v_readlane_b32 s59, v224, 21
	v_readlane_b32 s64, v224, 22
	v_readlane_b32 s65, v224, 23
	s_lshl_b32 s52, s51, 12
	s_add_u32 s58, s58, s52
	s_addc_u32 s59, s59, 0
	s_lshl_b32 s52, s51, 11
	s_add_u32 s64, s64, s52
	s_addc_u32 s65, s65, 0
	v_lshlrev_b32_e32 v248, 5, v197
	v_lshlrev_b32_e32 v249, 4, v197
	global_load_dwordx4 v[232:235], v248, s[58:59]
	global_load_dwordx4 v[236:239], v248, s[58:59] offset:16
	global_load_dwordx4 v[240:243], v248, s[58:59] offset:2048
	global_load_dwordx4 v[244:247], v248, s[58:59] offset:2064
